# barrier acquires: buffer_inv sc1 (L1 + L2 walk, ~1.1 us each) replaced by buffer_inv sc0 (L1) when every workgroup sits on XCC blockIdx%8 (verified at run time through the first grid barrier's flags,
# speedup vs baseline: 1.0223x; 1.0183x over previous
.LBB0_115:
	s_and_b64 vcc, exec, s[4:5]
	s_cbranch_vccz .LBB0_153
	s_waitcnt vmcnt(0)
	s_cmp_gt_u32 s60, 63
	s_barrier
	s_cbranch_scc1 .Lp1pf
	s_add_u32 s22, s34, 0x44000
	s_addc_u32 s23, s35, 0
	s_mov_b32 s3, 0
	v_cmp_eq_u32_e64 s[4:5], 0, v1
	s_and_saveexec_b64 s[6:7], s[4:5]
	s_cbranch_execz .LBB0_119
	s_lshl_b64 s[0:1], s[2:3], 2
	s_add_u32 s0, s22, s0
	s_addc_u32 s1, s23, s1
	v_mov_b32_e32 v2, 0
	v_readlane_b32 s100, v250, 12
	s_and_b32 s101, s2, 7
	s_cmp_lg_u32 s100, s101
	s_cselect_b32 s100, 0x101, 1
	v_mov_b32_e32 v3, s100
	global_store_dword v2, v3, s[0:1] sc1

.LBB0_122:
	global_load_dword v2, v[4:5], off sc1
	global_load_dword v6, v[4:5], off offset:256 sc1
	global_load_dword v7, v[4:5], off offset:512 sc1
	global_load_dword v8, v[4:5], off offset:768 sc1
	s_mov_b64 s[22:23], -1
	s_waitcnt vmcnt(0)
	v_max3_u32 v9, v2, v6, v7
	v_max_u32_e32 v9, v9, v8
	v_lshrrev_b32_e32 v9, 8, v9
	v_cmp_ne_u32_e64 s[100:101], 0, v9
	v_min_u32_e32 v2, v2, v6
	v_min3_u32 v2, v2, v7, v8
	v_cmp_eq_u32_e64 s[38:39], 0, v2
	v_cndmask_b32_e64 v2, 0, 1, s[38:39]
	v_cmp_ne_u32_e32 vcc, 0, v2
	s_mov_b64 s[24:25], -1
	s_cbranch_vccz .LBB0_121
	s_and_b32 s1, s0, 0xff
	s_cmp_eq_u32 s1, 0
	s_mov_b64 s[38:39], -1
	s_sleep 1
	s_cbranch_scc0 .LBB0_132
	global_load_dword v2, v3, s[34:35] sc1
	s_waitcnt vmcnt(0)
	v_cmp_eq_u32_e32 vcc, 0, v2
	s_cbranch_vccnz .LBB0_134
	s_mov_b64 s[38:39], 0

.LBB0_137:
	s_and_saveexec_b64 s[22:23], s[4:5]
	s_cbranch_execz .LBB0_139
	v_mov_b32_e32 v2, 0
	s_cmp_lg_u64 s[100:101], 0
	s_cselect_b32 s101, 0x101, 1
	v_mov_b32_e32 v3, s101
	global_store_dword v2, v3, s[6:7] sc1

.LBB0_151:
	s_waitcnt vmcnt(0)
	v_readfirstlane_b32 s100, v3
	s_and_b32 s100, s100, 0x100
	s_cmp_eq_u32 s100, 0
	s_cbranch_scc1 .Linv_l1_fb1
	buffer_inv sc1
	s_branch .Linv_done_fb1
.Linv_l1_fb1:
	buffer_inv sc0
.Linv_done_fb1:
	s_waitcnt vmcnt(0)
.LBB0_152:
	s_barrier

.LBB0_230:
	s_waitcnt vmcnt(0)
	s_cmp_eq_u32 s100, 0
	s_cbranch_scc1 .Linv_l1_tb1
	buffer_inv sc1
	s_branch .Linv_done_tb1

.Linv_done_tb1:
	s_waitcnt vmcnt(0)
.LBB0_231:
	s_or_b64 exec, exec, s[4:5]
	s_barrier

.Linv_done_tb2:
	s_waitcnt vmcnt(0)
.LBB0_382:
	s_or_b64 exec, exec, s[4:5]
	s_barrier

.Linv_done_fb2:
	s_waitcnt vmcnt(0)
.LBB0_543:
	s_barrier

.Linv_done_tb3:
	s_waitcnt vmcnt(0)
.LBB0_756:
	s_or_b64 exec, exec, s[6:7]
	s_barrier

.Linv_done_tb4:
	s_waitcnt vmcnt(0)
.LBB0_846:
	s_or_b64 exec, exec, s[6:7]
	s_barrier

	.amdhsa_kernel _Z6mk_fwd4Args
		.amdhsa_group_segment_fixed_size 0
		.amdhsa_private_segment_fixed_size 0
		.amdhsa_kernarg_size 440
		.amdhsa_user_sgpr_count 2
		.amdhsa_user_sgpr_dispatch_ptr 0
		.amdhsa_user_sgpr_queue_ptr 0
		.amdhsa_user_sgpr_kernarg_segment_ptr 1
		.amdhsa_user_sgpr_dispatch_id 0
		.amdhsa_user_sgpr_kernarg_preload_length 0
		.amdhsa_user_sgpr_kernarg_preload_offset 0
		.amdhsa_user_sgpr_private_segment_size 0
		.amdhsa_uses_dynamic_stack 0
		.amdhsa_enable_private_segment 0
		.amdhsa_system_sgpr_workgroup_id_x 1
		.amdhsa_system_sgpr_workgroup_id_y 0
		.amdhsa_system_sgpr_workgroup_id_z 0
		.amdhsa_system_sgpr_workgroup_info 0
		.amdhsa_system_vgpr_workitem_id 0
		.amdhsa_next_free_vgpr 251
		.amdhsa_next_free_sgpr 102
		.amdhsa_accum_offset 252
		.amdhsa_reserve_vcc 1
		.amdhsa_float_round_mode_32 0
		.amdhsa_float_round_mode_16_64 0
		.amdhsa_float_denorm_mode_32 3
		.amdhsa_float_denorm_mode_16_64 3
		.amdhsa_dx10_clamp 1
		.amdhsa_ieee_mode 1
		.amdhsa_fp16_overflow 0
		.amdhsa_tg_split 0
		.amdhsa_exception_fp_ieee_invalid_op 0
		.amdhsa_exception_fp_denorm_src 0
		.amdhsa_exception_fp_ieee_div_zero 0
		.amdhsa_exception_fp_ieee_overflow 0
		.amdhsa_exception_fp_ieee_underflow 0
		.amdhsa_exception_fp_ieee_inexact 0
		.amdhsa_exception_int_div_zero 0
	.end_amdhsa_kernel

amdhsa.kernels:
  - .agpr_count:     0
    .args:
      - .offset:         0
        .size:           184
        .value_kind:     by_value
      - .offset:         184
        .size:           4
        .value_kind:     hidden_block_count_x
      - .offset:         188
        .size:           4
        .value_kind:     hidden_block_count_y
      - .offset:         192
        .size:           4
        .value_kind:     hidden_block_count_z
      - .offset:         196
        .size:           2
        .value_kind:     hidden_group_size_x
      - .offset:         198
        .size:           2
        .value_kind:     hidden_group_size_y
      - .offset:         200
        .size:           2
        .value_kind:     hidden_group_size_z
      - .offset:         202
        .size:           2
        .value_kind:     hidden_remainder_x
      - .offset:         204
        .size:           2
        .value_kind:     hidden_remainder_y
      - .offset:         206
        .size:           2
        .value_kind:     hidden_remainder_z
      - .offset:         224
        .size:           8
        .value_kind:     hidden_global_offset_x
      - .offset:         232
        .size:           8
        .value_kind:     hidden_global_offset_y
      - .offset:         240
        .size:           8
        .value_kind:     hidden_global_offset_z
      - .offset:         248
        .size:           2
        .value_kind:     hidden_grid_dims
      - .offset:         304
        .size:           4
        .value_kind:     hidden_dynamic_lds_size
    .group_segment_fixed_size: 0
    .kernarg_segment_align: 8
    .kernarg_segment_size: 440
    .language:       OpenCL C
    .language_version:
      - 2
      - 0
    .max_flat_workgroup_size: 512
    .name:           _Z6mk_fwd4Args
    .private_segment_fixed_size: 0
    .sgpr_count:     108
    .sgpr_spill_count: 17
    .symbol:         _Z6mk_fwd4Args.kd
    .uniform_work_group_size: 1
    .uses_dynamic_stack: false
    .vgpr_count:     251
    .vgpr_spill_count: 0
    .wavefront_size: 64
